# opt27: opt26 + tile sb+2's K/V LDS-DMA pairs moved from after the QK blocks to the start of tile a's softmax
# baseline (speedup 1.0000x reference)
.LBB0_897:
	s_mov_b32 m0, s32
	s_nop 0
	global_load_lds_dwordx4 v164, s[98:99]
	s_add_i32 m0, s32, 0x400
	s_nop 0
	global_load_lds_dwordx4 v170, s[98:99]
	s_mov_b32 m0, s71
	s_nop 0
	global_load_lds_dwordx4 v168, s[100:101]
	s_add_i32 m0, s71, 0x400
	s_nop 0
	global_load_lds_dwordx4 v172, s[100:101]
	v_max_f32_e32 v174, v112, v113
	v_max_f32_e32 v179, v96, v97
	v_max3_f32 v174, v174, v114, v115
	v_max3_f32 v179, v179, v98, v99
	v_max3_f32 v174, v174, v116, v117
	v_max3_f32 v179, v179, v100, v101
	v_max3_f32 v174, v174, v118, v119
	v_max3_f32 v179, v179, v102, v103
	v_max3_f32 v174, v174, v120, v121
	v_max3_f32 v179, v179, v104, v105
	v_max3_f32 v174, v174, v122, v123
	v_max3_f32 v179, v179, v106, v107
	v_max3_f32 v174, v174, v124, v125
	v_max3_f32 v179, v179, v108, v109
	v_max3_f32 v174, v174, v126, v127
	v_max3_f32 v179, v179, v110, v111
	v_add_f32_e32 v174, v204, v174
	v_add_f32_e32 v179, v205, v179
	v_max_f32_e32 v174, v174, v179
	v_mov_b32_e32 v179, v174
	s_nop 1
	v_permlane32_swap_b32_e32 v174, v179
	v_max_f32_e32 v174, v174, v179
	v_sub_f32_e32 v179, v174, v203
	v_cmp_gt_f32_e32 vcc, s18, v179
	s_cmp_lg_u64 vcc, exec
	s_cselect_b64 s[82:83], -1, 0
	s_cmp_eq_u64 vcc, exec
	s_cbranch_scc1 .LBB0_901
	v_max_f32_e32 v144, v174, v174
	v_max_f32_e32 v145, v203, v203
	v_max_f32_e32 v174, v145, v144
	v_sub_f32_e32 v144, v203, v174
	v_exp_f32_e32 v144, v144
	s_nop 0
	v_cmp_neq_f32_e32 vcc, 1.0, v144
	s_cbranch_vccz .LBB0_900
	v_mul_f32_e32 v30, v144, v30
	v_mul_f32_e32 v31, v144, v31
	v_mul_f32_e32 v28, v144, v28
	v_mul_f32_e32 v29, v144, v29
	v_mul_f32_e32 v26, v144, v26
	v_mul_f32_e32 v27, v144, v27
	v_mul_f32_e32 v24, v144, v24
	v_mul_f32_e32 v25, v144, v25
	v_mul_f32_e32 v22, v144, v22
	v_mul_f32_e32 v23, v144, v23
	v_mul_f32_e32 v20, v144, v20
	v_mul_f32_e32 v21, v144, v21
	v_mul_f32_e32 v18, v144, v18
	v_mul_f32_e32 v19, v144, v19
	v_mul_f32_e32 v16, v144, v16
	v_mul_f32_e32 v17, v144, v17
	v_mul_f32_e32 v62, v144, v62
	v_mul_f32_e32 v63, v144, v63
	v_mul_f32_e32 v60, v144, v60
	v_mul_f32_e32 v61, v144, v61
	v_mul_f32_e32 v58, v144, v58
	v_mul_f32_e32 v59, v144, v59
	v_mul_f32_e32 v56, v144, v56
	v_mul_f32_e32 v57, v144, v57
	v_mul_f32_e32 v54, v144, v54
	v_mul_f32_e32 v55, v144, v55
	v_mul_f32_e32 v52, v144, v52
	v_mul_f32_e32 v53, v144, v53
	v_mul_f32_e32 v50, v144, v50
	v_mul_f32_e32 v51, v144, v51
	v_mul_f32_e32 v48, v144, v48
	v_mul_f32_e32 v49, v144, v49
	v_mul_f32_e32 v46, v144, v46
	v_mul_f32_e32 v47, v144, v47
	v_mul_f32_e32 v44, v144, v44
	v_mul_f32_e32 v45, v144, v45
	v_mul_f32_e32 v42, v144, v42
	v_mul_f32_e32 v43, v144, v43
	v_mul_f32_e32 v40, v144, v40
	v_mul_f32_e32 v41, v144, v41
	v_mul_f32_e32 v38, v144, v38
	v_mul_f32_e32 v39, v144, v39
	v_mul_f32_e32 v36, v144, v36
	v_mul_f32_e32 v37, v144, v37
	v_mul_f32_e32 v34, v144, v34
	v_mul_f32_e32 v35, v144, v35
	v_mul_f32_e32 v32, v144, v32
	v_mul_f32_e32 v33, v144, v33
	v_mul_f32_e32 v14, v144, v14
	v_mul_f32_e32 v15, v144, v15
	v_mul_f32_e32 v12, v144, v12
	v_mul_f32_e32 v13, v144, v13
	v_mul_f32_e32 v10, v144, v10
	v_mul_f32_e32 v11, v144, v11
	v_mul_f32_e32 v8, v144, v8
	v_mul_f32_e32 v9, v144, v9
	v_mul_f32_e32 v6, v144, v6
	v_mul_f32_e32 v7, v144, v7
	v_mul_f32_e32 v4, v144, v4
	v_mul_f32_e32 v5, v144, v5
	v_mul_f32_e32 v2, v144, v2
	v_mul_f32_e32 v3, v144, v3
	v_mul_f32_e32 v0, v144, v0
	v_mul_f32_e32 v1, v144, v1
